# adaLN k-step: the 9 pairs of LDS reads double-buffered (next pair issued before the current pair's 16 packed FMAs) instead of read-wait-use
# speedup vs baseline: 1.0159x; 1.0159x over previous
.LBB0_117:
	v_lshl_add_u32 v134, s28, 8, v181
	s_add_i32 s21, s21, 1
	s_cmp_eq_u32 s21, 32
	v_add_u32_e32 v144, v134, v184
	ds_read_b128 v[126:129], v144
	v_add_u32_e32 v145, v134, v185
	ds_read_b128 v[130:133], v145
	v_add_u32_e32 v144, v134, v186
	ds_read_b128 v[136:139], v144
	v_add_u32_e32 v145, v134, v187
	ds_read_b128 v[140:143], v145
	s_waitcnt lgkmcnt(2)
	s_waitcnt vmcnt(7)
	v_pk_fma_f32 v[80:81], v[30:31], v[126:127], v[80:81] op_sel_hi:[1,0,1]
	v_pk_fma_f32 v[76:77], v[32:33], v[126:127], v[76:77] op_sel_hi:[1,0,1]
	s_waitcnt vmcnt(5)
	v_pk_fma_f32 v[80:81], v[26:27], v[126:127], v[80:81] op_sel:[0,1,0]
	v_pk_fma_f32 v[76:77], v[28:29], v[126:127], v[76:77] op_sel:[0,1,0]
	v_pk_fma_f32 v[88:89], v[30:31], v[130:131], v[88:89] op_sel_hi:[1,0,1]
	v_pk_fma_f32 v[82:83], v[32:33], v[130:131], v[82:83] op_sel_hi:[1,0,1]
	s_waitcnt vmcnt(3)
	v_pk_fma_f32 v[80:81], v[22:23], v[128:129], v[80:81] op_sel_hi:[1,0,1]
	v_pk_fma_f32 v[76:77], v[24:25], v[128:129], v[76:77] op_sel_hi:[1,0,1]
	v_mov_b32_e32 v122, v129
	v_pk_fma_f32 v[82:83], v[28:29], v[130:131], v[82:83] op_sel:[0,1,0]
	v_pk_fma_f32 v[88:89], v[26:27], v[130:131], v[88:89] op_sel:[0,1,0]
	s_waitcnt vmcnt(1)
	v_pk_fma_f32 v[76:77], v[20:21], v[122:123], v[76:77] op_sel_hi:[1,0,1]
	v_pk_fma_f32 v[80:81], v[18:19], v[122:123], v[80:81] op_sel_hi:[1,0,1]
	v_pk_fma_f32 v[88:89], v[22:23], v[132:133], v[88:89] op_sel_hi:[1,0,1]
	v_pk_fma_f32 v[82:83], v[24:25], v[132:133], v[82:83] op_sel_hi:[1,0,1]
	v_mov_b32_e32 v122, v133
	v_pk_fma_f32 v[82:83], v[20:21], v[122:123], v[82:83] op_sel_hi:[1,0,1]
	v_pk_fma_f32 v[88:89], v[18:19], v[122:123], v[88:89] op_sel_hi:[1,0,1]
	v_add_u32_e32 v144, v134, v188
	ds_read_b128 v[126:129], v144
	v_add_u32_e32 v145, v134, v189
	ds_read_b128 v[130:133], v145
	s_waitcnt lgkmcnt(2)
	v_pk_fma_f32 v[72:73], v[30:31], v[136:137], v[72:73] op_sel_hi:[1,0,1]
	v_pk_fma_f32 v[68:69], v[32:33], v[136:137], v[68:69] op_sel_hi:[1,0,1]
	v_pk_fma_f32 v[72:73], v[26:27], v[136:137], v[72:73] op_sel:[0,1,0]
	v_pk_fma_f32 v[68:69], v[28:29], v[136:137], v[68:69] op_sel:[0,1,0]
	v_pk_fma_f32 v[78:79], v[30:31], v[140:141], v[78:79] op_sel_hi:[1,0,1]
	v_pk_fma_f32 v[74:75], v[32:33], v[140:141], v[74:75] op_sel_hi:[1,0,1]
	v_pk_fma_f32 v[72:73], v[22:23], v[138:139], v[72:73] op_sel_hi:[1,0,1]
	v_pk_fma_f32 v[68:69], v[24:25], v[138:139], v[68:69] op_sel_hi:[1,0,1]
	v_mov_b32_e32 v122, v139
	v_pk_fma_f32 v[74:75], v[28:29], v[140:141], v[74:75] op_sel:[0,1,0]
	v_pk_fma_f32 v[78:79], v[26:27], v[140:141], v[78:79] op_sel:[0,1,0]
	v_pk_fma_f32 v[68:69], v[20:21], v[122:123], v[68:69] op_sel_hi:[1,0,1]
	v_pk_fma_f32 v[72:73], v[18:19], v[122:123], v[72:73] op_sel_hi:[1,0,1]
	v_pk_fma_f32 v[78:79], v[22:23], v[142:143], v[78:79] op_sel_hi:[1,0,1]
	v_pk_fma_f32 v[74:75], v[24:25], v[142:143], v[74:75] op_sel_hi:[1,0,1]
	v_mov_b32_e32 v122, v143
	v_pk_fma_f32 v[74:75], v[20:21], v[122:123], v[74:75] op_sel_hi:[1,0,1]
	v_pk_fma_f32 v[78:79], v[18:19], v[122:123], v[78:79] op_sel_hi:[1,0,1]
	v_add_u32_e32 v144, v134, v190
	ds_read_b128 v[136:139], v144
	v_add_u32_e32 v145, v134, v191
	ds_read_b128 v[140:143], v145
	s_waitcnt lgkmcnt(2)
	v_pk_fma_f32 v[64:65], v[30:31], v[126:127], v[64:65] op_sel_hi:[1,0,1]
	v_pk_fma_f32 v[60:61], v[32:33], v[126:127], v[60:61] op_sel_hi:[1,0,1]
	v_pk_fma_f32 v[64:65], v[26:27], v[126:127], v[64:65] op_sel:[0,1,0]
	v_pk_fma_f32 v[60:61], v[28:29], v[126:127], v[60:61] op_sel:[0,1,0]
	v_pk_fma_f32 v[70:71], v[30:31], v[130:131], v[70:71] op_sel_hi:[1,0,1]
	v_pk_fma_f32 v[66:67], v[32:33], v[130:131], v[66:67] op_sel_hi:[1,0,1]
	v_pk_fma_f32 v[64:65], v[22:23], v[128:129], v[64:65] op_sel_hi:[1,0,1]
	v_pk_fma_f32 v[60:61], v[24:25], v[128:129], v[60:61] op_sel_hi:[1,0,1]
	v_mov_b32_e32 v122, v129
	v_pk_fma_f32 v[66:67], v[28:29], v[130:131], v[66:67] op_sel:[0,1,0]
	v_pk_fma_f32 v[70:71], v[26:27], v[130:131], v[70:71] op_sel:[0,1,0]
	v_pk_fma_f32 v[60:61], v[20:21], v[122:123], v[60:61] op_sel_hi:[1,0,1]
	v_pk_fma_f32 v[64:65], v[18:19], v[122:123], v[64:65] op_sel_hi:[1,0,1]
	v_pk_fma_f32 v[70:71], v[22:23], v[132:133], v[70:71] op_sel_hi:[1,0,1]
	v_pk_fma_f32 v[66:67], v[24:25], v[132:133], v[66:67] op_sel_hi:[1,0,1]
	v_mov_b32_e32 v122, v133
	v_pk_fma_f32 v[66:67], v[20:21], v[122:123], v[66:67] op_sel_hi:[1,0,1]
	v_pk_fma_f32 v[70:71], v[18:19], v[122:123], v[70:71] op_sel_hi:[1,0,1]
	v_add_u32_e32 v144, v134, v192
	ds_read_b128 v[126:129], v144
	v_add_u32_e32 v145, v134, v193
	ds_read_b128 v[130:133], v145
	s_waitcnt lgkmcnt(2)
	v_pk_fma_f32 v[56:57], v[30:31], v[136:137], v[56:57] op_sel_hi:[1,0,1]
	v_pk_fma_f32 v[54:55], v[32:33], v[136:137], v[54:55] op_sel_hi:[1,0,1]
	v_pk_fma_f32 v[56:57], v[26:27], v[136:137], v[56:57] op_sel:[0,1,0]
	v_pk_fma_f32 v[54:55], v[28:29], v[136:137], v[54:55] op_sel:[0,1,0]
	v_pk_fma_f32 v[62:63], v[30:31], v[140:141], v[62:63] op_sel_hi:[1,0,1]
	v_pk_fma_f32 v[58:59], v[32:33], v[140:141], v[58:59] op_sel_hi:[1,0,1]
	v_pk_fma_f32 v[56:57], v[22:23], v[138:139], v[56:57] op_sel_hi:[1,0,1]
	v_pk_fma_f32 v[54:55], v[24:25], v[138:139], v[54:55] op_sel_hi:[1,0,1]
	v_mov_b32_e32 v122, v139
	v_pk_fma_f32 v[58:59], v[28:29], v[140:141], v[58:59] op_sel:[0,1,0]
	v_pk_fma_f32 v[62:63], v[26:27], v[140:141], v[62:63] op_sel:[0,1,0]
	v_pk_fma_f32 v[54:55], v[20:21], v[122:123], v[54:55] op_sel_hi:[1,0,1]
	v_pk_fma_f32 v[56:57], v[18:19], v[122:123], v[56:57] op_sel_hi:[1,0,1]
	v_pk_fma_f32 v[62:63], v[22:23], v[142:143], v[62:63] op_sel_hi:[1,0,1]
	v_pk_fma_f32 v[58:59], v[24:25], v[142:143], v[58:59] op_sel_hi:[1,0,1]
	v_mov_b32_e32 v122, v143
	v_pk_fma_f32 v[58:59], v[20:21], v[122:123], v[58:59] op_sel_hi:[1,0,1]
	v_pk_fma_f32 v[62:63], v[18:19], v[122:123], v[62:63] op_sel_hi:[1,0,1]
	v_add_u32_e32 v144, v134, v194
	ds_read_b128 v[136:139], v144
	v_add_u32_e32 v145, v134, v195
	ds_read_b128 v[140:143], v145
	s_waitcnt lgkmcnt(2)
	v_pk_fma_f32 v[52:53], v[30:31], v[126:127], v[52:53] op_sel_hi:[1,0,1]
	v_pk_fma_f32 v[50:51], v[32:33], v[126:127], v[50:51] op_sel_hi:[1,0,1]
	v_pk_fma_f32 v[52:53], v[26:27], v[126:127], v[52:53] op_sel:[0,1,0]
	v_pk_fma_f32 v[50:51], v[28:29], v[126:127], v[50:51] op_sel:[0,1,0]
	v_pk_fma_f32 v[96:97], v[30:31], v[130:131], v[96:97] op_sel_hi:[1,0,1]
	v_pk_fma_f32 v[90:91], v[32:33], v[130:131], v[90:91] op_sel_hi:[1,0,1]
	v_pk_fma_f32 v[52:53], v[22:23], v[128:129], v[52:53] op_sel_hi:[1,0,1]
	v_pk_fma_f32 v[50:51], v[24:25], v[128:129], v[50:51] op_sel_hi:[1,0,1]
	v_mov_b32_e32 v122, v129
	v_pk_fma_f32 v[90:91], v[28:29], v[130:131], v[90:91] op_sel:[0,1,0]
	v_pk_fma_f32 v[96:97], v[26:27], v[130:131], v[96:97] op_sel:[0,1,0]
	v_pk_fma_f32 v[50:51], v[20:21], v[122:123], v[50:51] op_sel_hi:[1,0,1]
	v_pk_fma_f32 v[52:53], v[18:19], v[122:123], v[52:53] op_sel_hi:[1,0,1]
	v_pk_fma_f32 v[96:97], v[22:23], v[132:133], v[96:97] op_sel_hi:[1,0,1]
	v_pk_fma_f32 v[90:91], v[24:25], v[132:133], v[90:91] op_sel_hi:[1,0,1]
	v_mov_b32_e32 v122, v133
	v_pk_fma_f32 v[90:91], v[20:21], v[122:123], v[90:91] op_sel_hi:[1,0,1]
	v_pk_fma_f32 v[96:97], v[18:19], v[122:123], v[96:97] op_sel_hi:[1,0,1]
	v_add_u32_e32 v144, v134, v196
	ds_read_b128 v[126:129], v144
	v_add_u32_e32 v145, v134, v197
	ds_read_b128 v[130:133], v145
	s_waitcnt lgkmcnt(2)
	v_pk_fma_f32 v[86:87], v[30:31], v[136:137], v[86:87] op_sel_hi:[1,0,1]
	v_pk_fma_f32 v[84:85], v[32:33], v[136:137], v[84:85] op_sel_hi:[1,0,1]
	v_pk_fma_f32 v[86:87], v[26:27], v[136:137], v[86:87] op_sel:[0,1,0]
	v_pk_fma_f32 v[84:85], v[28:29], v[136:137], v[84:85] op_sel:[0,1,0]
	v_pk_fma_f32 v[104:105], v[30:31], v[140:141], v[104:105] op_sel_hi:[1,0,1]
	v_pk_fma_f32 v[98:99], v[32:33], v[140:141], v[98:99] op_sel_hi:[1,0,1]
	v_pk_fma_f32 v[86:87], v[22:23], v[138:139], v[86:87] op_sel_hi:[1,0,1]
	v_pk_fma_f32 v[84:85], v[24:25], v[138:139], v[84:85] op_sel_hi:[1,0,1]
	v_mov_b32_e32 v122, v139
	v_pk_fma_f32 v[98:99], v[28:29], v[140:141], v[98:99] op_sel:[0,1,0]
	v_pk_fma_f32 v[104:105], v[26:27], v[140:141], v[104:105] op_sel:[0,1,0]
	v_pk_fma_f32 v[84:85], v[20:21], v[122:123], v[84:85] op_sel_hi:[1,0,1]
	v_pk_fma_f32 v[86:87], v[18:19], v[122:123], v[86:87] op_sel_hi:[1,0,1]
	v_pk_fma_f32 v[104:105], v[22:23], v[142:143], v[104:105] op_sel_hi:[1,0,1]
	v_pk_fma_f32 v[98:99], v[24:25], v[142:143], v[98:99] op_sel_hi:[1,0,1]
	v_mov_b32_e32 v122, v143
	v_pk_fma_f32 v[98:99], v[20:21], v[122:123], v[98:99] op_sel_hi:[1,0,1]
	v_pk_fma_f32 v[104:105], v[18:19], v[122:123], v[104:105] op_sel_hi:[1,0,1]
	v_add_u32_e32 v144, v134, v198
	ds_read_b128 v[136:139], v144
	v_add_u32_e32 v145, v134, v199
	ds_read_b128 v[140:143], v145
	s_waitcnt lgkmcnt(2)
	v_pk_fma_f32 v[94:95], v[30:31], v[126:127], v[94:95] op_sel_hi:[1,0,1]
	v_pk_fma_f32 v[92:93], v[32:33], v[126:127], v[92:93] op_sel_hi:[1,0,1]
	v_pk_fma_f32 v[94:95], v[26:27], v[126:127], v[94:95] op_sel:[0,1,0]
	v_pk_fma_f32 v[92:93], v[28:29], v[126:127], v[92:93] op_sel:[0,1,0]
	v_pk_fma_f32 v[112:113], v[30:31], v[130:131], v[112:113] op_sel_hi:[1,0,1]
	v_pk_fma_f32 v[106:107], v[32:33], v[130:131], v[106:107] op_sel_hi:[1,0,1]
	v_pk_fma_f32 v[94:95], v[22:23], v[128:129], v[94:95] op_sel_hi:[1,0,1]
	v_pk_fma_f32 v[92:93], v[24:25], v[128:129], v[92:93] op_sel_hi:[1,0,1]
	v_mov_b32_e32 v122, v129
	v_pk_fma_f32 v[106:107], v[28:29], v[130:131], v[106:107] op_sel:[0,1,0]
	v_pk_fma_f32 v[112:113], v[26:27], v[130:131], v[112:113] op_sel:[0,1,0]
	v_pk_fma_f32 v[92:93], v[20:21], v[122:123], v[92:93] op_sel_hi:[1,0,1]
	v_pk_fma_f32 v[94:95], v[18:19], v[122:123], v[94:95] op_sel_hi:[1,0,1]
	v_pk_fma_f32 v[112:113], v[22:23], v[132:133], v[112:113] op_sel_hi:[1,0,1]
	v_pk_fma_f32 v[106:107], v[24:25], v[132:133], v[106:107] op_sel_hi:[1,0,1]
	v_mov_b32_e32 v122, v133
	v_pk_fma_f32 v[106:107], v[20:21], v[122:123], v[106:107] op_sel_hi:[1,0,1]
	v_pk_fma_f32 v[112:113], v[18:19], v[122:123], v[112:113] op_sel_hi:[1,0,1]
	v_add_u32_e32 v144, v134, v200
	ds_read_b128 v[126:129], v144
	v_add_u32_e32 v145, v134, v201
	ds_read_b128 v[130:133], v145
	s_waitcnt lgkmcnt(2)
	v_pk_fma_f32 v[102:103], v[30:31], v[136:137], v[102:103] op_sel_hi:[1,0,1]
	v_pk_fma_f32 v[100:101], v[32:33], v[136:137], v[100:101] op_sel_hi:[1,0,1]
	v_pk_fma_f32 v[102:103], v[26:27], v[136:137], v[102:103] op_sel:[0,1,0]
	v_pk_fma_f32 v[100:101], v[28:29], v[136:137], v[100:101] op_sel:[0,1,0]
	v_pk_fma_f32 v[120:121], v[30:31], v[140:141], v[120:121] op_sel_hi:[1,0,1]
	v_pk_fma_f32 v[116:117], v[32:33], v[140:141], v[116:117] op_sel_hi:[1,0,1]
	v_pk_fma_f32 v[102:103], v[22:23], v[138:139], v[102:103] op_sel_hi:[1,0,1]
	v_pk_fma_f32 v[100:101], v[24:25], v[138:139], v[100:101] op_sel_hi:[1,0,1]
	v_mov_b32_e32 v122, v139
	v_pk_fma_f32 v[116:117], v[28:29], v[140:141], v[116:117] op_sel:[0,1,0]
	v_pk_fma_f32 v[120:121], v[26:27], v[140:141], v[120:121] op_sel:[0,1,0]
	v_pk_fma_f32 v[100:101], v[20:21], v[122:123], v[100:101] op_sel_hi:[1,0,1]
	v_pk_fma_f32 v[102:103], v[18:19], v[122:123], v[102:103] op_sel_hi:[1,0,1]
	v_pk_fma_f32 v[120:121], v[22:23], v[142:143], v[120:121] op_sel_hi:[1,0,1]
	v_pk_fma_f32 v[116:117], v[24:25], v[142:143], v[116:117] op_sel_hi:[1,0,1]
	v_mov_b32_e32 v122, v143
	v_pk_fma_f32 v[116:117], v[20:21], v[122:123], v[116:117] op_sel_hi:[1,0,1]
	v_pk_fma_f32 v[120:121], v[18:19], v[122:123], v[120:121] op_sel_hi:[1,0,1]
	s_waitcnt lgkmcnt(0)
	v_pk_fma_f32 v[110:111], v[30:31], v[126:127], v[110:111] op_sel_hi:[1,0,1]
	v_pk_fma_f32 v[108:109], v[32:33], v[126:127], v[108:109] op_sel_hi:[1,0,1]
	v_pk_fma_f32 v[30:31], v[30:31], v[130:131], v[118:119] op_sel_hi:[1,0,1]
	v_pk_fma_f32 v[32:33], v[32:33], v[130:131], v[114:115] op_sel_hi:[1,0,1]
	v_pk_fma_f32 v[108:109], v[28:29], v[126:127], v[108:109] op_sel:[0,1,0]
	v_pk_fma_f32 v[110:111], v[26:27], v[126:127], v[110:111] op_sel:[0,1,0]
	v_pk_fma_f32 v[28:29], v[28:29], v[130:131], v[32:33] op_sel:[0,1,0]
	v_pk_fma_f32 v[26:27], v[26:27], v[130:131], v[30:31] op_sel:[0,1,0]
	v_pk_fma_f32 v[110:111], v[22:23], v[128:129], v[110:111] op_sel_hi:[1,0,1]
	v_pk_fma_f32 v[108:109], v[24:25], v[128:129], v[108:109] op_sel_hi:[1,0,1]
	v_mov_b32_e32 v122, v129
	v_pk_fma_f32 v[22:23], v[22:23], v[132:133], v[26:27] op_sel_hi:[1,0,1]
	v_pk_fma_f32 v[24:25], v[24:25], v[132:133], v[28:29] op_sel_hi:[1,0,1]
	v_mov_b32_e32 v26, v133
	v_pk_fma_f32 v[108:109], v[20:21], v[122:123], v[108:109] op_sel_hi:[1,0,1]
	v_pk_fma_f32 v[110:111], v[18:19], v[122:123], v[110:111] op_sel_hi:[1,0,1]
	v_pk_fma_f32 v[114:115], v[20:21], v[26:27], v[24:25] op_sel_hi:[1,0,1]
	v_pk_fma_f32 v[118:119], v[18:19], v[26:27], v[22:23] op_sel_hi:[1,0,1]
	s_waitcnt vmcnt(0)
	v_mov_b64_e32 v[20:21], v[16:17]
	v_mov_b64_e32 v[24:25], v[12:13]
	v_mov_b64_e32 v[28:29], v[8:9]
	v_mov_b64_e32 v[32:33], v[4:5]
	v_mov_b64_e32 v[18:19], v[14:15]
	v_mov_b64_e32 v[22:23], v[10:11]
	v_mov_b64_e32 v[26:27], v[6:7]
	v_mov_b64_e32 v[30:31], v[2:3]
	v_mov_b64_e32 v[14:15], v[46:47]
	v_mov_b64_e32 v[10:11], v[42:43]
	v_mov_b64_e32 v[6:7], v[38:39]
	v_mov_b64_e32 v[2:3], v[34:35]
	v_mov_b64_e32 v[16:17], v[48:49]
	v_mov_b64_e32 v[12:13], v[44:45]
	v_mov_b64_e32 v[8:9], v[40:41]
	v_mov_b64_e32 v[4:5], v[36:37]
	s_cbranch_scc1 .LBB0_131
